# prologue de-serialisation: silu(c) staging loop for the adaLN GEMV rewritten (scalar pointer loads, 36 loads in flight instead of 72 dependent round trips)
# speedup vs baseline: 1.0434x; 1.0109x over previous
; __device__ __forceinline__ float silu_(float x) { return x * __builtin_amdgcn_rcpf(1.f + __expf(-x)); }
; __device__ __forceinline__ void prologue_phase(KA A, LAS unsigned char* lds, int tid, int lane, int wave) {
;     ...
;             if (!have_sc) {
;                 for (int i = tid; i < NBB * 1024; i += NTHREADS) { const int bb = i >> 10, k = i & 1023; const float c = bb < 2 ? A->in[7][bb * 1024 + k] : A->in[8][(bb - 2) * 1024 + k]; sc[i] = silu_(c); }
;                 have_sc = true;
;             }
.LBB0_20:
	s_and_b64 vcc, exec, s[22:23]
	s_cbranch_vccnz .LBB0_24
	s_load_dwordx4 s[44:47], s[14:15], 0x38
	v_mov_b32_e32 v0, v19
	v_add_u32_e32 v1, 0x10000, v19
	s_waitcnt lgkmcnt(0)
	global_load_dword v56, v0, s[44:45]
	global_load_dword v57, v0, s[44:45] offset:2048
	s_add_u32 s44, s44, 0x1000
	s_addc_u32 s45, s45, 0
	global_load_dword v58, v0, s[44:45]
	global_load_dword v59, v0, s[44:45] offset:2048
	global_load_dword v60, v0, s[46:47]
	global_load_dword v61, v0, s[46:47] offset:2048
	s_add_u32 s46, s46, 0x1000
	s_addc_u32 s47, s47, 0
	global_load_dword v62, v0, s[46:47]
	global_load_dword v63, v0, s[46:47] offset:2048
	s_add_u32 s46, s46, 0x1000
	s_addc_u32 s47, s47, 0
	global_load_dword v64, v0, s[46:47]
	global_load_dword v65, v0, s[46:47] offset:2048
	s_add_u32 s46, s46, 0x1000
	s_addc_u32 s47, s47, 0
	global_load_dword v66, v0, s[46:47]
	global_load_dword v67, v0, s[46:47] offset:2048
	s_add_u32 s46, s46, 0x1000
	s_addc_u32 s47, s47, 0
	global_load_dword v68, v0, s[46:47]
	global_load_dword v69, v0, s[46:47] offset:2048
	s_add_u32 s46, s46, 0x1000
	s_addc_u32 s47, s47, 0
	global_load_dword v70, v0, s[46:47]
	global_load_dword v71, v0, s[46:47] offset:2048
	s_add_u32 s46, s46, 0x1000
	s_addc_u32 s47, s47, 0
	global_load_dword v72, v0, s[46:47]
	global_load_dword v73, v0, s[46:47] offset:2048
	s_add_u32 s46, s46, 0x1000
	s_addc_u32 s47, s47, 0
	global_load_dword v74, v0, s[46:47]
	global_load_dword v75, v0, s[46:47] offset:2048
	s_add_u32 s46, s46, 0x1000
	s_addc_u32 s47, s47, 0
	global_load_dword v76, v0, s[46:47]
	global_load_dword v77, v0, s[46:47] offset:2048
	s_add_u32 s46, s46, 0x1000
	s_addc_u32 s47, s47, 0
	global_load_dword v78, v0, s[46:47]
	global_load_dword v79, v0, s[46:47] offset:2048
	s_add_u32 s46, s46, 0x1000
	s_addc_u32 s47, s47, 0
	global_load_dword v80, v0, s[46:47]
	global_load_dword v81, v0, s[46:47] offset:2048
	s_add_u32 s46, s46, 0x1000
	s_addc_u32 s47, s47, 0
	global_load_dword v82, v0, s[46:47]
	global_load_dword v83, v0, s[46:47] offset:2048
	s_add_u32 s46, s46, 0x1000
	s_addc_u32 s47, s47, 0
	global_load_dword v84, v0, s[46:47]
	global_load_dword v85, v0, s[46:47] offset:2048
	s_add_u32 s46, s46, 0x1000
	s_addc_u32 s47, s47, 0
	global_load_dword v86, v0, s[46:47]
	global_load_dword v87, v0, s[46:47] offset:2048
	s_add_u32 s46, s46, 0x1000
	s_addc_u32 s47, s47, 0
	global_load_dword v88, v0, s[46:47]
	global_load_dword v89, v0, s[46:47] offset:2048
	s_add_u32 s46, s46, 0x1000
	s_addc_u32 s47, s47, 0
	global_load_dword v90, v0, s[46:47]
	global_load_dword v91, v0, s[46:47] offset:2048
	s_add_u32 s46, s46, 0x1000
	s_addc_u32 s47, s47, 0
	s_waitcnt vmcnt(35)
	v_mul_f32_e32 v2, 0xbfb8aa3b, v56
	v_exp_f32_e32 v2, v2
	s_nop 0
	v_add_f32_e32 v2, 1.0, v2
	v_rcp_f32_e32 v2, v2
	s_nop 0
	v_mul_f32_e32 v56, v56, v2
	ds_write_b32 v0, v56
	s_waitcnt vmcnt(34)
	v_mul_f32_e32 v3, 0xbfb8aa3b, v57
	v_exp_f32_e32 v3, v3
	s_nop 0
	v_add_f32_e32 v3, 1.0, v3
	v_rcp_f32_e32 v3, v3
	s_nop 0
	v_mul_f32_e32 v57, v57, v3
	ds_write_b32 v0, v57 offset:2048
	s_waitcnt vmcnt(33)
	v_mul_f32_e32 v2, 0xbfb8aa3b, v58
	v_exp_f32_e32 v2, v2
	s_nop 0
	v_add_f32_e32 v2, 1.0, v2
	v_rcp_f32_e32 v2, v2
	s_nop 0
	v_mul_f32_e32 v58, v58, v2
	ds_write_b32 v0, v58 offset:4096
	s_waitcnt vmcnt(32)
	v_mul_f32_e32 v3, 0xbfb8aa3b, v59
	v_exp_f32_e32 v3, v3
	s_nop 0
	v_add_f32_e32 v3, 1.0, v3
	v_rcp_f32_e32 v3, v3
	s_nop 0
	v_mul_f32_e32 v59, v59, v3
	ds_write_b32 v0, v59 offset:6144
	s_waitcnt vmcnt(31)
	v_mul_f32_e32 v2, 0xbfb8aa3b, v60
	v_exp_f32_e32 v2, v2
	s_nop 0
	v_add_f32_e32 v2, 1.0, v2
	v_rcp_f32_e32 v2, v2
	s_nop 0
	v_mul_f32_e32 v60, v60, v2
	ds_write_b32 v0, v60 offset:8192
	s_waitcnt vmcnt(30)
	v_mul_f32_e32 v3, 0xbfb8aa3b, v61
	v_exp_f32_e32 v3, v3
	s_nop 0
	v_add_f32_e32 v3, 1.0, v3
	v_rcp_f32_e32 v3, v3
	s_nop 0
	v_mul_f32_e32 v61, v61, v3
	ds_write_b32 v0, v61 offset:10240
	s_waitcnt vmcnt(29)
	v_mul_f32_e32 v2, 0xbfb8aa3b, v62
	v_exp_f32_e32 v2, v2
	s_nop 0
	v_add_f32_e32 v2, 1.0, v2
	v_rcp_f32_e32 v2, v2
	s_nop 0
	v_mul_f32_e32 v62, v62, v2
	ds_write_b32 v0, v62 offset:12288
	s_waitcnt vmcnt(28)
	v_mul_f32_e32 v3, 0xbfb8aa3b, v63
	v_exp_f32_e32 v3, v3
	s_nop 0
	v_add_f32_e32 v3, 1.0, v3
	v_rcp_f32_e32 v3, v3
	s_nop 0
	v_mul_f32_e32 v63, v63, v3
	ds_write_b32 v0, v63 offset:14336
	s_waitcnt vmcnt(27)
	v_mul_f32_e32 v2, 0xbfb8aa3b, v64
	v_exp_f32_e32 v2, v2
	s_nop 0
	v_add_f32_e32 v2, 1.0, v2
	v_rcp_f32_e32 v2, v2
	s_nop 0
	v_mul_f32_e32 v64, v64, v2
	ds_write_b32 v0, v64 offset:16384
	s_waitcnt vmcnt(26)
	v_mul_f32_e32 v3, 0xbfb8aa3b, v65
	v_exp_f32_e32 v3, v3
	s_nop 0
	v_add_f32_e32 v3, 1.0, v3
	v_rcp_f32_e32 v3, v3
	s_nop 0
	v_mul_f32_e32 v65, v65, v3
	ds_write_b32 v0, v65 offset:18432
	s_waitcnt vmcnt(25)
	v_mul_f32_e32 v2, 0xbfb8aa3b, v66
	v_exp_f32_e32 v2, v2
	s_nop 0
	v_add_f32_e32 v2, 1.0, v2
	v_rcp_f32_e32 v2, v2
	s_nop 0
	v_mul_f32_e32 v66, v66, v2
	ds_write_b32 v0, v66 offset:20480
	s_waitcnt vmcnt(24)
	v_mul_f32_e32 v3, 0xbfb8aa3b, v67
	v_exp_f32_e32 v3, v3
	s_nop 0
	v_add_f32_e32 v3, 1.0, v3
	v_rcp_f32_e32 v3, v3
	s_nop 0
	v_mul_f32_e32 v67, v67, v3
	ds_write_b32 v0, v67 offset:22528
	s_waitcnt vmcnt(23)
; __device__ __forceinline__ float silu_(float x) { return x * __builtin_amdgcn_rcpf(1.f + __expf(-x)); }
; __device__ __forceinline__ void prologue_phase(KA A, LAS unsigned char* lds, int tid, int lane, int wave) {
;     ...
;                 for (int i = tid; i < NBB * 1024; i += NTHREADS) { const int bb = i >> 10, k = i & 1023; const float c = bb < 2 ? A->in[7][bb * 1024 + k] : A->in[8][(bb - 2) * 1024 + k]; sc[i] = silu_(c); }
;                 have_sc = true;
	v_mul_f32_e32 v2, 0xbfb8aa3b, v68
	v_exp_f32_e32 v2, v2
	s_nop 0
	v_add_f32_e32 v2, 1.0, v2
	v_rcp_f32_e32 v2, v2
	s_nop 0
	v_mul_f32_e32 v68, v68, v2
	ds_write_b32 v0, v68 offset:24576
	s_waitcnt vmcnt(22)
	v_mul_f32_e32 v3, 0xbfb8aa3b, v69
	v_exp_f32_e32 v3, v3
	s_nop 0
	v_add_f32_e32 v3, 1.0, v3
	v_rcp_f32_e32 v3, v3
	s_nop 0
	v_mul_f32_e32 v69, v69, v3
	ds_write_b32 v0, v69 offset:26624
	s_waitcnt vmcnt(21)
	v_mul_f32_e32 v2, 0xbfb8aa3b, v70
	v_exp_f32_e32 v2, v2
	s_nop 0
	v_add_f32_e32 v2, 1.0, v2
	v_rcp_f32_e32 v2, v2
	s_nop 0
	v_mul_f32_e32 v70, v70, v2
	ds_write_b32 v0, v70 offset:28672
	s_waitcnt vmcnt(20)
	v_mul_f32_e32 v3, 0xbfb8aa3b, v71
	v_exp_f32_e32 v3, v3
	s_nop 0
	v_add_f32_e32 v3, 1.0, v3
	v_rcp_f32_e32 v3, v3
	s_nop 0
	v_mul_f32_e32 v71, v71, v3
	ds_write_b32 v0, v71 offset:30720
	s_waitcnt vmcnt(19)
	v_mul_f32_e32 v2, 0xbfb8aa3b, v72
	v_exp_f32_e32 v2, v2
	s_nop 0
	v_add_f32_e32 v2, 1.0, v2
	v_rcp_f32_e32 v2, v2
	s_nop 0
	v_mul_f32_e32 v72, v72, v2
	ds_write_b32 v0, v72 offset:32768
	s_waitcnt vmcnt(18)
	v_mul_f32_e32 v3, 0xbfb8aa3b, v73
	v_exp_f32_e32 v3, v3
	s_nop 0
	v_add_f32_e32 v3, 1.0, v3
	v_rcp_f32_e32 v3, v3
	s_nop 0
	v_mul_f32_e32 v73, v73, v3
	ds_write_b32 v0, v73 offset:34816
	s_waitcnt vmcnt(17)
	v_mul_f32_e32 v2, 0xbfb8aa3b, v74
	v_exp_f32_e32 v2, v2
	s_nop 0
	v_add_f32_e32 v2, 1.0, v2
	v_rcp_f32_e32 v2, v2
	s_nop 0
	v_mul_f32_e32 v74, v74, v2
	ds_write_b32 v0, v74 offset:36864
	s_waitcnt vmcnt(16)
	v_mul_f32_e32 v3, 0xbfb8aa3b, v75
	v_exp_f32_e32 v3, v3
	s_nop 0
	v_add_f32_e32 v3, 1.0, v3
	v_rcp_f32_e32 v3, v3
	s_nop 0
	v_mul_f32_e32 v75, v75, v3
	ds_write_b32 v0, v75 offset:38912
	s_waitcnt vmcnt(15)
	v_mul_f32_e32 v2, 0xbfb8aa3b, v76
	v_exp_f32_e32 v2, v2
	s_nop 0
	v_add_f32_e32 v2, 1.0, v2
	v_rcp_f32_e32 v2, v2
	s_nop 0
	v_mul_f32_e32 v76, v76, v2
	ds_write_b32 v0, v76 offset:40960
	s_waitcnt vmcnt(14)
	v_mul_f32_e32 v3, 0xbfb8aa3b, v77
	v_exp_f32_e32 v3, v3
	s_nop 0
	v_add_f32_e32 v3, 1.0, v3
	v_rcp_f32_e32 v3, v3
	s_nop 0
	v_mul_f32_e32 v77, v77, v3
	ds_write_b32 v0, v77 offset:43008
	s_waitcnt vmcnt(13)
	v_mul_f32_e32 v2, 0xbfb8aa3b, v78
	v_exp_f32_e32 v2, v2
	s_nop 0
	v_add_f32_e32 v2, 1.0, v2
	v_rcp_f32_e32 v2, v2
	s_nop 0
	v_mul_f32_e32 v78, v78, v2
	ds_write_b32 v0, v78 offset:45056
	s_waitcnt vmcnt(12)
	v_mul_f32_e32 v3, 0xbfb8aa3b, v79
	v_exp_f32_e32 v3, v3
	s_nop 0
	v_add_f32_e32 v3, 1.0, v3
	v_rcp_f32_e32 v3, v3
	s_nop 0
	v_mul_f32_e32 v79, v79, v3
	ds_write_b32 v0, v79 offset:47104
	s_waitcnt vmcnt(11)
	v_mul_f32_e32 v2, 0xbfb8aa3b, v80
	v_exp_f32_e32 v2, v2
	s_nop 0
	v_add_f32_e32 v2, 1.0, v2
	v_rcp_f32_e32 v2, v2
	s_nop 0
	v_mul_f32_e32 v80, v80, v2
	ds_write_b32 v0, v80 offset:49152
	s_waitcnt vmcnt(10)
	v_mul_f32_e32 v3, 0xbfb8aa3b, v81
	v_exp_f32_e32 v3, v3
	s_nop 0
	v_add_f32_e32 v3, 1.0, v3
	v_rcp_f32_e32 v3, v3
	s_nop 0
	v_mul_f32_e32 v81, v81, v3
	ds_write_b32 v0, v81 offset:51200
	s_waitcnt vmcnt(9)
	v_mul_f32_e32 v2, 0xbfb8aa3b, v82
	v_exp_f32_e32 v2, v2
	s_nop 0
	v_add_f32_e32 v2, 1.0, v2
	v_rcp_f32_e32 v2, v2
	s_nop 0
	v_mul_f32_e32 v82, v82, v2
	ds_write_b32 v0, v82 offset:53248
	s_waitcnt vmcnt(8)
	v_mul_f32_e32 v3, 0xbfb8aa3b, v83
	v_exp_f32_e32 v3, v3
	s_nop 0
	v_add_f32_e32 v3, 1.0, v3
	v_rcp_f32_e32 v3, v3
	s_nop 0
	v_mul_f32_e32 v83, v83, v3
	ds_write_b32 v0, v83 offset:55296
	s_waitcnt vmcnt(7)
	v_mul_f32_e32 v2, 0xbfb8aa3b, v84
	v_exp_f32_e32 v2, v2
	s_nop 0
	v_add_f32_e32 v2, 1.0, v2
	v_rcp_f32_e32 v2, v2
	s_nop 0
	v_mul_f32_e32 v84, v84, v2
	ds_write_b32 v0, v84 offset:57344
	s_waitcnt vmcnt(6)
	v_mul_f32_e32 v3, 0xbfb8aa3b, v85
	v_exp_f32_e32 v3, v3
	s_nop 0
	v_add_f32_e32 v3, 1.0, v3
	v_rcp_f32_e32 v3, v3
	s_nop 0
	v_mul_f32_e32 v85, v85, v3
	ds_write_b32 v0, v85 offset:59392
	s_waitcnt vmcnt(5)
	v_mul_f32_e32 v2, 0xbfb8aa3b, v86
	v_exp_f32_e32 v2, v2
	s_nop 0
	v_add_f32_e32 v2, 1.0, v2
	v_rcp_f32_e32 v2, v2
	s_nop 0
	v_mul_f32_e32 v86, v86, v2
	ds_write_b32 v0, v86 offset:61440
	s_waitcnt vmcnt(4)
	v_mul_f32_e32 v3, 0xbfb8aa3b, v87
	v_exp_f32_e32 v3, v3
	s_nop 0
	v_add_f32_e32 v3, 1.0, v3
	v_rcp_f32_e32 v3, v3
	s_nop 0
	v_mul_f32_e32 v87, v87, v3
	ds_write_b32 v0, v87 offset:63488
	s_waitcnt vmcnt(3)
	v_mul_f32_e32 v2, 0xbfb8aa3b, v88
	v_exp_f32_e32 v2, v2
	s_nop 0
	v_add_f32_e32 v2, 1.0, v2
	v_rcp_f32_e32 v2, v2
	s_nop 0
	v_mul_f32_e32 v88, v88, v2
	ds_write_b32 v1, v88
	s_waitcnt vmcnt(2)
	v_mul_f32_e32 v3, 0xbfb8aa3b, v89
	v_exp_f32_e32 v3, v3
	s_nop 0
	v_add_f32_e32 v3, 1.0, v3
	v_rcp_f32_e32 v3, v3
	s_nop 0
	v_mul_f32_e32 v89, v89, v3
	ds_write_b32 v1, v89 offset:2048
	s_waitcnt vmcnt(1)
	v_mul_f32_e32 v2, 0xbfb8aa3b, v90
	v_exp_f32_e32 v2, v2
	s_nop 0
	v_add_f32_e32 v2, 1.0, v2
	v_rcp_f32_e32 v2, v2
	s_nop 0
	v_mul_f32_e32 v90, v90, v2
	ds_write_b32 v1, v90 offset:4096
	s_waitcnt vmcnt(0)
	v_mul_f32_e32 v3, 0xbfb8aa3b, v91
	v_exp_f32_e32 v3, v3
	s_nop 0
	v_add_f32_e32 v3, 1.0, v3
	v_rcp_f32_e32 v3, v3
	s_nop 0
	v_mul_f32_e32 v91, v91, v3
	ds_write_b32 v1, v91 offset:6144
	s_mov_b64 s[22:23], exec
